# K-loop: scalar constants moved behind the SP1 LDS reads so every load segment starts with its fragment reads
# speedup vs baseline: 1.0032x; 1.0032x over previous
; #define PG8_STAGE(bufoff, gbase, voff) do { _Pragma("unroll") for (int _i = 0; _i < 2; ++_i) \
;         __builtin_amdgcn_global_load_lds((const unsigned*)((const char*)(gbase) + (voff)[_i]), (PG8_LAS unsigned*)(lds + (bufoff) + ldsw + _i * 8192), 16, 0, 0); } while (0)
; #define PG8_LDA(dst, b, h) do { _Pragma("unroll") for (int m = 0; m < 4; ++m) _Pragma("unroll") for (int k = 0; k < 2; ++k) dst[m][k] = *(const PG8_LAS bf16x8*)(lds + PG8_SA(b, h) + aoff + m * 2048 + k * 1024); } while (0)
; #define PG8_LDB(dst, b, h) do { _Pragma("unroll") for (int n = 0; n < 2; ++n) _Pragma("unroll") for (int k = 0; k < 2; ++k) dst[n][k] = *(const PG8_LAS bf16x8*)(lds + PG8_SB(b, h) + boff + n * 2048 + k * 1024); } while (0)
; #define PG8_MMA(ai, bj, At, Bt) do { __builtin_amdgcn_s_setprio(1); _Pragma("unroll") for (int m = 0; m < 4; ++m) _Pragma("unroll") for (int n = 0; n < 2; ++n) _Pragma("unroll") for (int k = 0; k < 2; ++k) \
;         acc[ai][bj][m][n] = __builtin_amdgcn_mfma_f32_16x16x32_bf16(Bt[n][k], At[m][k], acc[ai][bj][m][n], 0, 0, 0); __builtin_amdgcn_s_setprio(0); } while (0)
; #define PG8_WAIT_V(n) asm volatile("s_waitcnt vmcnt(" #n ")" ::: "memory")
; #define PG8_WAIT_L(n) asm volatile("s_waitcnt lgkmcnt(" #n ")" ::: "memory")
; #define PG8_BAR __builtin_amdgcn_s_barrier()
; #define PG8_SCHED __builtin_amdgcn_sched_barrier(0)
; template <class Epi, class Sched, bool ALIGN_EPI = false, bool SP2 = false>
; __device__ __forceinline__ void gemm_phase(PG8_LAS unsigned char* lds, const Gemm g, const Sched& S, const Epi& E) {
;     ...
;             const bool last = (t == nt - 2);
;             const char* a1 = cA + (size_t)(t + 1) * kstep;
;             const char* a2 = last ? nA : cA + (size_t)(t + 2) * kstep; const char* b2 = last ? nB : cB + (size_t)(t + 2) * kstep;
;             const char* a3 = a2 + kstep; const char* b3 = b2 + kstep;
;             if (last && has_next) S.a_ready(nxt);
;             if constexpr (SP2) {
;             PG8_LDB(B0, 0, 0); PG8_LDB(B1, 0, 1); PG8_SCHED; PG8_LDA(At, 0, 0); PG8_STAGE(PG8_SA(1, 1), a1 + hstep, voffA);
;             PG8_WAIT_V(8); PG8_WAIT_L(0); PG8_BAR; PG8_MMA(0, 0, At, B0); PG8_MMA(0, 1, At, B1); PG8_BAR; PG8_SCHED;
;             PG8_LDA(At, 0, 1); PG8_STAGE(PG8_SB(0, 0), b2, voffB); PG8_STAGE(PG8_SB(0, 1), b2 + hstep, voffB); PG8_STAGE(PG8_SA(0, 0), a2, voffA);
.LBB0_441:
	ds_read_b128 v[130:133], v242
	ds_read_b128 v[134:137], v242 offset:1024
	ds_read_b128 v[138:141], v242 offset:2048
	ds_read_b128 v[142:145], v242 offset:3072
	ds_read_b128 v[146:149], v243
	ds_read_b128 v[150:153], v243 offset:1024
	ds_read_b128 v[154:157], v243 offset:2048
	ds_read_b128 v[158:161], v243 offset:3072
	s_add_i32 s66, 0, 0x10000
	s_add_i32 s67, 0, 0x14000
	v_lshl_add_u64 v[206:207], s[42:43], 0, v[190:191]
	s_add_i32 m0, s93, 0xc000
	ds_read_b128 v[162:165], v230
	ds_read_b128 v[166:169], v230 offset:1024
	ds_read_b128 v[170:173], v230 offset:2048
	ds_read_b128 v[174:177], v230 offset:3072
	ds_read_b128 v[178:181], v230 offset:4096
	ds_read_b128 v[194:197], v230 offset:5120
	ds_read_b128 v[198:201], v230 offset:6144
	ds_read_b128 v[202:205], v230 offset:7168
	s_add_i32 s61, s44, 2
	s_add_u32 s64, s42, 0x80
	s_addc_u32 s45, s43, 0
	s_cmp_eq_u32 s99, s44
	s_cselect_b32 s45, s29, s45
	s_cselect_b32 s44, s28, s64
	s_cselect_b32 s65, s21, s60
	s_cselect_b32 s64, s20, s17
	global_load_lds_dwordx4 v[206:207], off
	s_add_i32 m0, s93, 0xe000
	v_lshl_add_u64 v[206:207], s[42:43], 0, v[192:193]
	global_load_lds_dwordx4 v[206:207], off
	s_setprio 1
	s_waitcnt vmcnt(8) lgkmcnt(0)
	s_barrier
	v_mfma_f32_16x16x32_bf16 v[126:129], v[130:133], v[162:165], v[126:129]
	v_mfma_f32_16x16x32_bf16 v[122:125], v[138:141], v[162:165], v[122:125]
	v_mfma_f32_16x16x32_bf16 v[110:113], v[130:133], v[170:173], v[110:113]
	v_mfma_f32_16x16x32_bf16 v[102:105], v[138:141], v[170:173], v[102:105]
	v_mfma_f32_16x16x32_bf16 v[94:97], v[130:133], v[178:181], v[94:97]
	v_mfma_f32_16x16x32_bf16 v[86:89], v[138:141], v[178:181], v[86:89]
	v_mfma_f32_16x16x32_bf16 v[78:81], v[130:133], v[198:201], v[78:81]
	v_mfma_f32_16x16x32_bf16 v[70:73], v[138:141], v[198:201], v[70:73]
	v_mfma_f32_16x16x32_bf16 v[126:129], v[134:137], v[166:169], v[126:129]
	v_mfma_f32_16x16x32_bf16 v[122:125], v[142:145], v[166:169], v[122:125]
	v_mfma_f32_16x16x32_bf16 v[110:113], v[134:137], v[174:177], v[110:113]
	v_mfma_f32_16x16x32_bf16 v[102:105], v[142:145], v[174:177], v[102:105]
	v_mfma_f32_16x16x32_bf16 v[94:97], v[134:137], v[194:197], v[94:97]
	v_mfma_f32_16x16x32_bf16 v[86:89], v[142:145], v[194:197], v[86:89]
	v_mfma_f32_16x16x32_bf16 v[78:81], v[134:137], v[202:205], v[78:81]
	v_mfma_f32_16x16x32_bf16 v[70:73], v[142:145], v[202:205], v[70:73]
	v_mfma_f32_16x16x32_bf16 v[118:121], v[146:149], v[162:165], v[118:121]
	v_mfma_f32_16x16x32_bf16 v[114:117], v[154:157], v[162:165], v[114:117]
	v_mfma_f32_16x16x32_bf16 v[106:109], v[146:149], v[170:173], v[106:109]
	v_mfma_f32_16x16x32_bf16 v[98:101], v[154:157], v[170:173], v[98:101]
	v_mfma_f32_16x16x32_bf16 v[90:93], v[146:149], v[178:181], v[90:93]
	v_mfma_f32_16x16x32_bf16 v[82:85], v[154:157], v[178:181], v[82:85]
	v_mfma_f32_16x16x32_bf16 v[74:77], v[146:149], v[198:201], v[74:77]
	v_mfma_f32_16x16x32_bf16 v[66:69], v[154:157], v[198:201], v[66:69]
	v_mfma_f32_16x16x32_bf16 v[118:121], v[150:153], v[166:169], v[118:121]
	v_mfma_f32_16x16x32_bf16 v[114:117], v[158:161], v[166:169], v[114:117]
	v_mfma_f32_16x16x32_bf16 v[106:109], v[150:153], v[174:177], v[106:109]
	v_mfma_f32_16x16x32_bf16 v[98:101], v[158:161], v[174:177], v[98:101]
	v_mfma_f32_16x16x32_bf16 v[90:93], v[150:153], v[194:197], v[90:93]
	v_mfma_f32_16x16x32_bf16 v[82:85], v[158:161], v[194:197], v[82:85]
	v_mfma_f32_16x16x32_bf16 v[74:77], v[150:153], v[202:205], v[74:77]
	v_mfma_f32_16x16x32_bf16 v[66:69], v[158:161], v[202:205], v[66:69]
	s_barrier
	s_setprio 0
	ds_read_b128 v[162:165], v230 offset:16384
	ds_read_b128 v[166:169], v230 offset:17408
	ds_read_b128 v[170:173], v230 offset:18432
	ds_read_b128 v[174:177], v230 offset:19456
	ds_read_b128 v[178:181], v230 offset:20480
	ds_read_b128 v[194:197], v230 offset:21504
	ds_read_b128 v[198:201], v230 offset:22528
	ds_read_b128 v[202:205], v230 offset:23552
	s_add_i32 s66, s66, s92
	s_mov_b32 m0, s66
	v_lshl_add_u64 v[206:207], s[64:65], 0, v[184:185]
	global_load_lds_dwordx4 v[206:207], off
	s_add_i32 m0, s66, 0x2000
	v_lshl_add_u64 v[208:209], s[64:65], 0, v[188:189]
	s_add_u32 s64, s64, s26
	s_addc_u32 s65, s65, 0
	s_add_i32 s66, s67, s92
	global_load_lds_dwordx4 v[208:209], off
	v_lshl_add_u64 v[210:211], s[64:65], 0, v[184:185]
	s_mov_b32 m0, s66
	v_lshl_add_u64 v[232:233], s[64:65], 0, v[188:189]
	global_load_lds_dwordx4 v[210:211], off
	s_add_i32 m0, s66, 0x2000
	v_lshl_add_u64 v[234:235], s[44:45], 0, v[182:183]
	global_load_lds_dwordx4 v[232:233], off
	s_mov_b32 m0, s93
	v_lshl_add_u64 v[236:237], s[44:45], 0, v[186:187]
	global_load_lds_dwordx4 v[234:235], off
	s_mov_b32 m0, s94
	s_nop 0
	global_load_lds_dwordx4 v[236:237], off
	s_setprio 1
	s_waitcnt vmcnt(8) lgkmcnt(0)
	s_barrier
; #define PG8_STAGE(bufoff, gbase, voff) do { _Pragma("unroll") for (int _i = 0; _i < 2; ++_i) \
;         __builtin_amdgcn_global_load_lds((const unsigned*)((const char*)(gbase) + (voff)[_i]), (PG8_LAS unsigned*)(lds + (bufoff) + ldsw + _i * 8192), 16, 0, 0); } while (0)
; #define PG8_LDA(dst, b, h) do { _Pragma("unroll") for (int m = 0; m < 4; ++m) _Pragma("unroll") for (int k = 0; k < 2; ++k) dst[m][k] = *(const PG8_LAS bf16x8*)(lds + PG8_SA(b, h) + aoff + m * 2048 + k * 1024); } while (0)
; #define PG8_LDB(dst, b, h) do { _Pragma("unroll") for (int n = 0; n < 2; ++n) _Pragma("unroll") for (int k = 0; k < 2; ++k) dst[n][k] = *(const PG8_LAS bf16x8*)(lds + PG8_SB(b, h) + boff + n * 2048 + k * 1024); } while (0)
; #define PG8_MMA(ai, bj, At, Bt) do { __builtin_amdgcn_s_setprio(1); _Pragma("unroll") for (int m = 0; m < 4; ++m) _Pragma("unroll") for (int n = 0; n < 2; ++n) _Pragma("unroll") for (int k = 0; k < 2; ++k) \
;         acc[ai][bj][m][n] = __builtin_amdgcn_mfma_f32_16x16x32_bf16(Bt[n][k], At[m][k], acc[ai][bj][m][n], 0, 0, 0); __builtin_amdgcn_s_setprio(0); } while (0)
; #define PG8_WAIT_V(n) asm volatile("s_waitcnt vmcnt(" #n ")" ::: "memory")
; #define PG8_WAIT_L(n) asm volatile("s_waitcnt lgkmcnt(" #n ")" ::: "memory")
; #define PG8_BAR __builtin_amdgcn_s_barrier()
; #define PG8_SCHED __builtin_amdgcn_sched_barrier(0)
; template <class Epi, class Sched, bool ALIGN_EPI = false, bool SP2 = false>
; __device__ __forceinline__ void gemm_phase(PG8_LAS unsigned char* lds, const Gemm g, const Sched& S, const Epi& E) {
;     ...
;             PG8_WAIT_V(8); PG8_WAIT_L(0); PG8_BAR; PG8_MMA(1, 0, At, B0); PG8_MMA(1, 1, At, B1); PG8_BAR; PG8_SCHED;
;             PG8_LDB(B0, 1, 0); PG8_LDB(B1, 1, 1); PG8_SCHED; PG8_LDA(At, 1, 0); PG8_STAGE(PG8_SA(0, 1), a2 + hstep, voffA);
;             PG8_WAIT_V(8); PG8_WAIT_L(0); PG8_BAR; PG8_MMA(0, 0, At, B0); PG8_MMA(0, 1, At, B1); PG8_BAR; PG8_SCHED;
	v_mfma_f32_16x16x32_bf16 v[62:65], v[130:133], v[162:165], v[62:65]
	v_mfma_f32_16x16x32_bf16 v[54:57], v[138:141], v[162:165], v[54:57]
	v_mfma_f32_16x16x32_bf16 v[46:49], v[130:133], v[170:173], v[46:49]
	v_mfma_f32_16x16x32_bf16 v[38:41], v[138:141], v[170:173], v[38:41]
	v_mfma_f32_16x16x32_bf16 v[30:33], v[130:133], v[178:181], v[30:33]
	v_mfma_f32_16x16x32_bf16 v[22:25], v[138:141], v[178:181], v[22:25]
	v_mfma_f32_16x16x32_bf16 v[14:17], v[130:133], v[198:201], v[14:17]
	v_mfma_f32_16x16x32_bf16 v[6:9], v[138:141], v[198:201], v[6:9]
	v_mfma_f32_16x16x32_bf16 v[62:65], v[134:137], v[166:169], v[62:65]
	v_mfma_f32_16x16x32_bf16 v[54:57], v[142:145], v[166:169], v[54:57]
	v_mfma_f32_16x16x32_bf16 v[46:49], v[134:137], v[174:177], v[46:49]
	v_mfma_f32_16x16x32_bf16 v[38:41], v[142:145], v[174:177], v[38:41]
	v_mfma_f32_16x16x32_bf16 v[30:33], v[134:137], v[194:197], v[30:33]
	v_mfma_f32_16x16x32_bf16 v[22:25], v[142:145], v[194:197], v[22:25]
	v_mfma_f32_16x16x32_bf16 v[14:17], v[134:137], v[202:205], v[14:17]
	v_mfma_f32_16x16x32_bf16 v[6:9], v[142:145], v[202:205], v[6:9]
	v_mfma_f32_16x16x32_bf16 v[58:61], v[146:149], v[162:165], v[58:61]
	v_mfma_f32_16x16x32_bf16 v[50:53], v[154:157], v[162:165], v[50:53]
	v_mfma_f32_16x16x32_bf16 v[42:45], v[146:149], v[170:173], v[42:45]
	v_mfma_f32_16x16x32_bf16 v[34:37], v[154:157], v[170:173], v[34:37]
	v_mfma_f32_16x16x32_bf16 v[26:29], v[146:149], v[178:181], v[26:29]
	v_mfma_f32_16x16x32_bf16 v[18:21], v[154:157], v[178:181], v[18:21]
	v_mfma_f32_16x16x32_bf16 v[10:13], v[146:149], v[198:201], v[10:13]
	v_mfma_f32_16x16x32_bf16 v[2:5], v[154:157], v[198:201], v[2:5]
	v_mfma_f32_16x16x32_bf16 v[58:61], v[150:153], v[166:169], v[58:61]
	v_mfma_f32_16x16x32_bf16 v[50:53], v[158:161], v[166:169], v[50:53]
	v_mfma_f32_16x16x32_bf16 v[42:45], v[150:153], v[174:177], v[42:45]
	v_mfma_f32_16x16x32_bf16 v[34:37], v[158:161], v[174:177], v[34:37]
	v_mfma_f32_16x16x32_bf16 v[26:29], v[150:153], v[194:197], v[26:29]
	v_mfma_f32_16x16x32_bf16 v[18:21], v[158:161], v[194:197], v[18:21]
	v_mfma_f32_16x16x32_bf16 v[10:13], v[150:153], v[202:205], v[10:13]
	v_mfma_f32_16x16x32_bf16 v[2:5], v[158:161], v[202:205], v[2:5]
	s_barrier
	s_setprio 0
	ds_read_b128 v[162:165], v230 offset:32768
	ds_read_b128 v[166:169], v230 offset:33792
	ds_read_b128 v[170:173], v230 offset:34816
	ds_read_b128 v[174:177], v230 offset:35840
	ds_read_b128 v[178:181], v230 offset:36864
	ds_read_b128 v[194:197], v230 offset:37888
	ds_read_b128 v[198:201], v230 offset:38912
	ds_read_b128 v[202:205], v230 offset:39936
	ds_read_b128 v[130:133], v244
	ds_read_b128 v[134:137], v244 offset:1024
	ds_read_b128 v[138:141], v244 offset:2048
	ds_read_b128 v[142:145], v244 offset:3072
	ds_read_b128 v[146:149], v245
	ds_read_b128 v[150:153], v245 offset:1024
	ds_read_b128 v[154:157], v245 offset:2048
	ds_read_b128 v[158:161], v245 offset:3072
	s_add_i32 s64, 0, 0x18000
	s_add_i32 s65, 0, 0x1c000
	s_add_u32 s44, s44, s26
	s_addc_u32 s45, s45, 0
	s_mov_b32 m0, s95
	v_lshl_add_u64 v[238:239], s[44:45], 0, v[182:183]
	global_load_lds_dwordx4 v[238:239], off
	s_mov_b32 m0, s96
	v_lshl_add_u64 v[238:239], s[44:45], 0, v[186:187]
	global_load_lds_dwordx4 v[238:239], off
	s_setprio 1
	s_waitcnt vmcnt(8) lgkmcnt(0)
	s_barrier
	v_mfma_f32_16x16x32_bf16 v[126:129], v[130:133], v[162:165], v[126:129]
	v_mfma_f32_16x16x32_bf16 v[122:125], v[138:141], v[162:165], v[122:125]
	v_mfma_f32_16x16x32_bf16 v[110:113], v[130:133], v[170:173], v[110:113]
	v_mfma_f32_16x16x32_bf16 v[102:105], v[138:141], v[170:173], v[102:105]
	v_mfma_f32_16x16x32_bf16 v[94:97], v[130:133], v[178:181], v[94:97]
	v_mfma_f32_16x16x32_bf16 v[86:89], v[138:141], v[178:181], v[86:89]
	v_mfma_f32_16x16x32_bf16 v[78:81], v[130:133], v[198:201], v[78:81]
	v_mfma_f32_16x16x32_bf16 v[70:73], v[138:141], v[198:201], v[70:73]
	v_mfma_f32_16x16x32_bf16 v[126:129], v[134:137], v[166:169], v[126:129]
	v_mfma_f32_16x16x32_bf16 v[122:125], v[142:145], v[166:169], v[122:125]
	v_mfma_f32_16x16x32_bf16 v[110:113], v[134:137], v[174:177], v[110:113]
	v_mfma_f32_16x16x32_bf16 v[102:105], v[142:145], v[174:177], v[102:105]
	v_mfma_f32_16x16x32_bf16 v[94:97], v[134:137], v[194:197], v[94:97]
	v_mfma_f32_16x16x32_bf16 v[86:89], v[142:145], v[194:197], v[86:89]
	v_mfma_f32_16x16x32_bf16 v[78:81], v[134:137], v[202:205], v[78:81]
	v_mfma_f32_16x16x32_bf16 v[70:73], v[142:145], v[202:205], v[70:73]
	v_mfma_f32_16x16x32_bf16 v[118:121], v[146:149], v[162:165], v[118:121]
	v_mfma_f32_16x16x32_bf16 v[114:117], v[154:157], v[162:165], v[114:117]
	v_mfma_f32_16x16x32_bf16 v[106:109], v[146:149], v[170:173], v[106:109]
	v_mfma_f32_16x16x32_bf16 v[98:101], v[154:157], v[170:173], v[98:101]
	v_mfma_f32_16x16x32_bf16 v[90:93], v[146:149], v[178:181], v[90:93]
	v_mfma_f32_16x16x32_bf16 v[82:85], v[154:157], v[178:181], v[82:85]
	v_mfma_f32_16x16x32_bf16 v[74:77], v[146:149], v[198:201], v[74:77]
	v_mfma_f32_16x16x32_bf16 v[66:69], v[154:157], v[198:201], v[66:69]
	v_mfma_f32_16x16x32_bf16 v[118:121], v[150:153], v[166:169], v[118:121]
	v_mfma_f32_16x16x32_bf16 v[114:117], v[158:161], v[166:169], v[114:117]
	v_mfma_f32_16x16x32_bf16 v[106:109], v[150:153], v[174:177], v[106:109]
	v_mfma_f32_16x16x32_bf16 v[98:101], v[158:161], v[174:177], v[98:101]
	v_mfma_f32_16x16x32_bf16 v[90:93], v[150:153], v[194:197], v[90:93]
	v_mfma_f32_16x16x32_bf16 v[82:85], v[158:161], v[194:197], v[82:85]
	v_mfma_f32_16x16x32_bf16 v[74:77], v[150:153], v[202:205], v[74:77]
	v_mfma_f32_16x16x32_bf16 v[66:69], v[158:161], v[202:205], v[66:69]
	s_barrier
; #define PG8_STAGE(bufoff, gbase, voff) do { _Pragma("unroll") for (int _i = 0; _i < 2; ++_i) \
;         __builtin_amdgcn_global_load_lds((const unsigned*)((const char*)(gbase) + (voff)[_i]), (PG8_LAS unsigned*)(lds + (bufoff) + ldsw + _i * 8192), 16, 0, 0); } while (0)
; #define PG8_LDA(dst, b, h) do { _Pragma("unroll") for (int m = 0; m < 4; ++m) _Pragma("unroll") for (int k = 0; k < 2; ++k) dst[m][k] = *(const PG8_LAS bf16x8*)(lds + PG8_SA(b, h) + aoff + m * 2048 + k * 1024); } while (0)
; #define PG8_MMA(ai, bj, At, Bt) do { __builtin_amdgcn_s_setprio(1); _Pragma("unroll") for (int m = 0; m < 4; ++m) _Pragma("unroll") for (int n = 0; n < 2; ++n) _Pragma("unroll") for (int k = 0; k < 2; ++k) \
;         acc[ai][bj][m][n] = __builtin_amdgcn_mfma_f32_16x16x32_bf16(Bt[n][k], At[m][k], acc[ai][bj][m][n], 0, 0, 0); __builtin_amdgcn_s_setprio(0); } while (0)
; #define PG8_WAIT_V(n) asm volatile("s_waitcnt vmcnt(" #n ")" ::: "memory")
; #define PG8_WAIT_L(n) asm volatile("s_waitcnt lgkmcnt(" #n ")" ::: "memory")
; #define PG8_BAR __builtin_amdgcn_s_barrier()
; #define PG8_SCHED __builtin_amdgcn_sched_barrier(0)
; template <class Epi, class Sched, bool ALIGN_EPI = false, bool SP2 = false>
; __device__ __forceinline__ void gemm_phase(PG8_LAS unsigned char* lds, const Gemm g, const Sched& S, const Epi& E) {
;     ...
;             PG8_LDA(At, 1, 1); PG8_STAGE(PG8_SB(1, 0), b3, voffB); PG8_STAGE(PG8_SB(1, 1), b3 + hstep, voffB); PG8_STAGE(PG8_SA(1, 0), a3, voffA);
;             PG8_WAIT_V(8); PG8_WAIT_L(0); PG8_BAR; PG8_MMA(1, 0, At, B0); PG8_MMA(1, 1, At, B1); PG8_BAR; PG8_SCHED;
;     ...
;         if constexpr (ALIGN_EPI) { if (wr == 0) PG8_BAR; }
;         if constexpr (!Epi::AFTER_DRAIN) { E(acc, cur, wr, wc, fr, fq); S.done(cur); }
	s_setprio 0
	ds_read_b128 v[162:165], v230 offset:49152
	ds_read_b128 v[166:169], v230 offset:50176
	ds_read_b128 v[170:173], v230 offset:51200
	ds_read_b128 v[174:177], v230 offset:52224
	ds_read_b128 v[178:181], v230 offset:53248
	ds_read_b128 v[194:197], v230 offset:54272
	ds_read_b128 v[198:201], v230 offset:55296
	ds_read_b128 v[202:205], v230 offset:56320
	s_add_i32 s44, s64, s92
	s_mov_b32 m0, s44
	v_lshl_add_u64 v[206:207], v[206:207], 0, s[34:35]
	global_load_lds_dwordx4 v[206:207], off
	v_lshl_add_u64 v[206:207], v[208:209], 0, s[34:35]
	s_add_i32 m0, s44, 0x2000
	s_add_i32 s44, s65, s92
	global_load_lds_dwordx4 v[206:207], off
	s_mov_b32 m0, s44
	v_lshl_add_u64 v[206:207], v[210:211], 0, s[34:35]
	global_load_lds_dwordx4 v[206:207], off
	s_add_i32 m0, s44, 0x2000
	v_lshl_add_u64 v[206:207], v[232:233], 0, s[34:35]
	global_load_lds_dwordx4 v[206:207], off
	s_mov_b32 m0, s97
	v_lshl_add_u64 v[206:207], v[234:235], 0, s[34:35]
	global_load_lds_dwordx4 v[206:207], off
	s_mov_b32 m0, s98
	v_lshl_add_u64 v[206:207], v[236:237], 0, s[34:35]
	global_load_lds_dwordx4 v[206:207], off
	s_add_u32 s42, s42, 0x100
	s_addc_u32 s43, s43, 0
	s_add_u32 s17, s17, 0x100
	s_addc_u32 s60, s60, 0
	s_cmp_ge_u32 s61, s4
	s_mov_b32 s44, s61
	s_setprio 1
	s_waitcnt vmcnt(8) lgkmcnt(0)
	s_barrier
	v_mfma_f32_16x16x32_bf16 v[62:65], v[130:133], v[162:165], v[62:65]
	v_mfma_f32_16x16x32_bf16 v[54:57], v[138:141], v[162:165], v[54:57]
	v_mfma_f32_16x16x32_bf16 v[46:49], v[130:133], v[170:173], v[46:49]
	v_mfma_f32_16x16x32_bf16 v[38:41], v[138:141], v[170:173], v[38:41]
	v_mfma_f32_16x16x32_bf16 v[30:33], v[130:133], v[178:181], v[30:33]
	v_mfma_f32_16x16x32_bf16 v[22:25], v[138:141], v[178:181], v[22:25]
	v_mfma_f32_16x16x32_bf16 v[14:17], v[130:133], v[198:201], v[14:17]
	v_mfma_f32_16x16x32_bf16 v[6:9], v[138:141], v[198:201], v[6:9]
	v_mfma_f32_16x16x32_bf16 v[62:65], v[134:137], v[166:169], v[62:65]
	v_mfma_f32_16x16x32_bf16 v[54:57], v[142:145], v[166:169], v[54:57]
	v_mfma_f32_16x16x32_bf16 v[46:49], v[134:137], v[174:177], v[46:49]
	v_mfma_f32_16x16x32_bf16 v[38:41], v[142:145], v[174:177], v[38:41]
	v_mfma_f32_16x16x32_bf16 v[30:33], v[134:137], v[194:197], v[30:33]
	v_mfma_f32_16x16x32_bf16 v[22:25], v[142:145], v[194:197], v[22:25]
	v_mfma_f32_16x16x32_bf16 v[14:17], v[134:137], v[202:205], v[14:17]
	v_mfma_f32_16x16x32_bf16 v[6:9], v[142:145], v[202:205], v[6:9]
	v_mfma_f32_16x16x32_bf16 v[58:61], v[146:149], v[162:165], v[58:61]
	v_mfma_f32_16x16x32_bf16 v[50:53], v[154:157], v[162:165], v[50:53]
	v_mfma_f32_16x16x32_bf16 v[42:45], v[146:149], v[170:173], v[42:45]
	v_mfma_f32_16x16x32_bf16 v[34:37], v[154:157], v[170:173], v[34:37]
	v_mfma_f32_16x16x32_bf16 v[26:29], v[146:149], v[178:181], v[26:29]
	v_mfma_f32_16x16x32_bf16 v[18:21], v[154:157], v[178:181], v[18:21]
	v_mfma_f32_16x16x32_bf16 v[10:13], v[146:149], v[198:201], v[10:13]
	v_mfma_f32_16x16x32_bf16 v[2:5], v[154:157], v[198:201], v[2:5]
	v_mfma_f32_16x16x32_bf16 v[58:61], v[150:153], v[166:169], v[58:61]
	v_mfma_f32_16x16x32_bf16 v[50:53], v[158:161], v[166:169], v[50:53]
	v_mfma_f32_16x16x32_bf16 v[42:45], v[150:153], v[174:177], v[42:45]
	v_mfma_f32_16x16x32_bf16 v[34:37], v[158:161], v[174:177], v[34:37]
	v_mfma_f32_16x16x32_bf16 v[26:29], v[150:153], v[194:197], v[26:29]
	v_mfma_f32_16x16x32_bf16 v[18:21], v[158:161], v[194:197], v[18:21]
	v_mfma_f32_16x16x32_bf16 v[10:13], v[150:153], v[202:205], v[10:13]
	v_mfma_f32_16x16x32_bf16 v[2:5], v[158:161], v[202:205], v[2:5]
	s_barrier
	s_setprio 0
	s_cbranch_scc0 .LBB0_441
	s_and_b64 vcc, exec, s[36:37]
	s_cbranch_vccz .LBB0_445
	s_barrier
	s_cmp_lt_i32 s0, 2
	s_mov_b64 s[42:43], -1
	s_cbranch_scc0 .LBB0_446
